# phase 0: odd waves run their task list rotated by two so HBM-streaming and L2/VALU-bound task types overlap
# baseline (speedup 1.0000x reference)
.LBB0_21:
	s_or_b64 exec, exec, s[6:7]
	s_waitcnt lgkmcnt(0)
	s_barrier
	s_load_dword s7, s[4:5], 0x0
	v_mov_b32_e32 v129, 0
	s_waitcnt lgkmcnt(0)
	s_cmp_lt_u32 s2, s7
	s_cselect_b32 s6, 12, 18
	s_add_u32 s12, s4, s6
	s_addc_u32 s13, s5, 0
	global_load_ushort v1, v129, s[12:13]
	s_mov_b32 s13, 0
	s_waitcnt vmcnt(0)
	v_readfirstlane_b32 s6, v1
	s_and_b32 s12, 0xffff, s6
	s_mul_i32 s6, s2, s12
	v_add_u32_e32 v1, s6, v0
	s_nop 0
	v_readfirstlane_b32 s6, v1
	s_cmp_gt_u32 s6, 0x109fff
	s_cbranch_scc1 .LBB0_116
	s_load_dword s4, s[4:5], 0x10
	v_and_b32_e32 v130, 63, v0
	v_lshlrev_b32_e32 v132, 2, v130
	v_lshrrev_b32_e32 v3, 1, v0
	v_lshlrev_b32_e32 v1, 5, v0
	s_waitcnt lgkmcnt(0)
	s_lshr_b32 s4, s4, 16
	s_and_b32 s4, s4, 0xffff
	s_cmp_lg_u32 s4, 0
	s_cselect_b64 s[4:5], -1, 0
	s_cmp_lg_u64 s[4:5], 0
	v_and_b32_e32 v2, 16, v132
	v_and_b32_e32 v3, 12, v3
	v_and_b32_e32 v0, 35, v0
	s_addc_u32 s4, s7, 0
	v_or3_b32 v151, v0, v3, v2
	v_mbcnt_lo_u32_b32 v0, -1, 0
	v_and_b32_e32 v1, 0xfffff800, v1
	s_mul_i32 s47, s4, s12
	v_mbcnt_hi_u32_b32 v0, -1, v0
	v_add_u32_e32 v1, 0, v1
	s_lshr_b32 s15, s47, 6
	s_lshr_b32 s17, s6, 6
	s_and_b32 s46, s6, 0xffffffc0
	v_lshlrev_b32_e32 v0, 2, v0
	v_and_b32_e32 v131, 0x80, v132
	v_add_u32_e32 v149, v1, v132
	s_add_i32 s19, s17, 0xffffde80
	s_lshl_b32 s23, s17, 2
	s_lshl_b32 s25, s15, 2
	s_andn2_b32 s47, s47, 63
	v_or_b32_e32 v153, v2, v3
	s_add_i32 s48, s17, 0xffffdf00
	s_add_i32 s14, s17, 0xffffe000
	s_add_i32 s49, s17, 0xffffe200
	s_add_i32 s51, s17, 0xfffff600
	s_add_i32 s52, s46, 0xfffd8000
	s_movk_i32 s53, 0x4000
	v_add_u32_e32 v155, 0x4000, v1
	v_mov_b32_e32 v133, v129
	s_add_i32 s54, s17, 0xfffffa00
	v_or_b32_e32 v134, 0x18000, v132
	v_mov_b32_e32 v135, v129
	s_brev_b32 s16, 60
	s_movk_i32 s55, 0x2000
	s_movk_i32 s56, 0x3000
	s_mov_b32 s57, 0x9000
	s_mov_b32 s58, 0xb000
	s_mov_b32 s59, 0xd000
	s_mov_b32 s62, 0xf000
	s_mov_b32 s63, 0x11000
	s_mov_b32 s64, 0x13000
	s_mov_b32 s65, 0x15000
	s_mov_b32 s66, 0x17000
	s_mov_b32 s67, 0x19000
	s_mov_b32 s68, 0x1b000
	s_mov_b32 s69, 0x1d000
	s_mov_b32 s70, 0x1f000
	s_mov_b32 s71, 0xfffeb000
	s_mov_b32 s72, 0xfffee000
	s_mov_b32 s73, 0xffff1000
	s_mov_b32 s74, 0xffff4000
	s_mov_b32 s75, 0xffff7000
	s_movk_i32 s76, 0xa000
	v_mov_b32_e32 v157, 0x3e3
	v_and_b32_e32 v159, 0x100, v0
	s_movk_i32 s77, 0xd000
	s_brev_b32 s18, 61
	s_mov_b64 s[20:21], 0x33fe000
	s_mov_b32 s22, 0x3b3504f3
	s_mov_b32 s24, 0xbb3504f3
	s_mov_b64 s[26:27], 0x1bfe620
	s_mov_b64 s[28:29], 0x20000
	s_mov_b64 s[30:31], 0x1bfe420
	s_mov_b64 s[34:35], 0x1bfe020
	s_mov_b64 s[36:37], 0x1ffe020
	s_mov_b64 s[38:39], 0x2fe020
	s_mov_b64 s[40:41], 0x30000
	s_mov_b32 s4, 0x4280
	s_bitcmp1_b32 s17, 0
	s_cselect_b32 s5, 1, 0
	s_nop 0
	v_writelane_b32 v255, s17, 61
	v_writelane_b32 v255, s4, 63
	v_writelane_b32 v255, s5, 62
	s_cbranch_scc0 .Lp0_norot
	s_lshl_b32 s4, s15, 1
	s_add_i32 s17, s17, s4
	s_add_i32 s19, s19, s4
	s_add_i32 s48, s48, s4
	s_add_i32 s14, s14, s4
	s_add_i32 s49, s49, s4
	s_add_i32 s51, s51, s4
	s_add_i32 s54, s54, s4
	s_lshl_b32 s5, s25, 1
	s_add_i32 s23, s23, s5
	s_lshl_b32 s5, s47, 1
	s_add_i32 s46, s46, s5
	s_add_i32 s52, s52, s5
.Lp0_norot:
	s_branch .LBB0_25
.LBB0_23:
	s_add_u32 s4, s42, s78
	s_addc_u32 s5, s43, 0
	s_add_u32 s4, s4, s12
	s_addc_u32 s5, s5, 0
	v_lshl_add_u64 v[2:3], s[4:5], 0, v[128:129]
	s_waitcnt vmcnt(0)
	v_add_f32_e32 v4, v9, v0
	v_add_co_u32_e32 v0, vcc, 0x1ec000, v2
	s_nop 1
	v_addc_co_u32_e32 v1, vcc, 0, v3, vcc
	global_atomic_add_f32 v[0:1], v4, off
.LBB0_24:
	s_add_i32 s17, s17, s15
	s_add_i32 s19, s19, s15
	s_add_i32 s23, s23, s25
	s_add_i32 s46, s46, s47
	s_add_i32 s48, s48, s15
	s_add_i32 s14, s14, s15
	s_add_i32 s49, s49, s15
	s_add_i32 s51, s51, s15
	s_add_i32 s52, s52, s47
	s_add_i32 s54, s54, s15
	v_readlane_b32 s4, v255, 63
	s_nop 3
	s_cmp_lt_u32 s17, s4
	s_cbranch_scc1 .LBB0_25
	v_readlane_b32 s5, v255, 62
	s_nop 3
	s_cmp_eq_u32 s5, 0
	s_cbranch_scc1 .LBB0_116
	v_readlane_b32 s17, v255, 61
	s_nop 3
	s_lshl_b32 s46, s17, 6
	s_add_i32 s19, s17, 0xffffde80
	s_lshl_b32 s23, s17, 2
	s_add_i32 s48, s17, 0xffffdf00
	s_add_i32 s14, s17, 0xffffe000
	s_add_i32 s49, s17, 0xffffe200
	s_add_i32 s51, s17, 0xfffff600
	s_add_i32 s52, s46, 0xfffd8000
	s_add_i32 s54, s17, 0xfffffa00
	s_lshl_b32 s4, s15, 1
	s_add_i32 s4, s4, s17
	s_mov_b32 s5, 0
	s_nop 0
	v_writelane_b32 v255, s4, 63
	v_writelane_b32 v255, s5, 62
	s_branch .LBB0_25
